# layer-0 w_up/w_down weight conversions moved from prep phase into slack of 96 in-proj blocks with 4 tiles
# baseline (speedup 1.0000x reference)
.LBB0_8:
	v_writelane_b32 v255, 0, 63
	v_writelane_b32 v255, 0, 61
	v_writelane_b32 v255, 0, 62
	s_add_u32 s0, s0, 0x120
	s_addc_u32 s1, s1, 0
	v_writelane_b32 v253, s0, 4
	v_lshrrev_b32_e32 v1, 20, v0
	v_lshrrev_b32_e32 v0, 10, v0
	v_writelane_b32 v253, s1, 5
	s_and_b32 s0, s52, 7
	v_writelane_b32 v253, s0, 6
	s_lshr_b32 s0, s52, 3
	v_writelane_b32 v253, s0, 7
	s_lshl_b32 s0, s52, 3
	s_cmpk_lt_i32 s52, 0x510
	v_writelane_b32 v253, s0, 8
	s_cselect_b64 s[0:1], -1, 0
	v_writelane_b32 v253, s0, 9
	s_cmp_gt_i32 s52, 31
	v_or_b32_e32 v0, v0, v1
	v_writelane_b32 v253, s1, 10
	s_cselect_b64 s[0:1], -1, 0
	v_writelane_b32 v253, s0, 11
	s_cmpk_lt_u32 s52, 0x510
	s_mov_b32 s54, s52
	v_writelane_b32 v253, s1, 12
	s_cselect_b64 s[0:1], -1, 0
	v_writelane_b32 v253, s0, 13
	s_ashr_i32 s53, s52, 31
	s_lshl_b64 s[6:7], s[52:53], 18
	v_writelane_b32 v253, s1, 14
	s_sub_i32 s0, s52, 32
	v_writelane_b32 v253, s0, 15
	v_writelane_b32 v253, s6, 16
	s_lshl_b32 s0, s52, 6
	v_mbcnt_lo_u32_b32 v2, -1, 0
	v_writelane_b32 v253, s7, 17
	s_lshl_b64 s[6:7], s[52:53], 17
	v_writelane_b32 v253, s6, 18
	s_mov_b32 s53, s0
	s_lshl_b32 s0, s52, 9
	v_writelane_b32 v253, s7, 19
	v_writelane_b32 v253, s0, 20
	s_add_u32 s0, s2, 0x11a48200
	s_addc_u32 s1, s3, 0
	v_writelane_b32 v253, s0, 21
	v_mbcnt_hi_u32_b32 v172, -1, v2
	v_and_b32_e32 v2, 64, v172
	v_writelane_b32 v253, s1, 22
	s_add_u32 s0, s2, 0x11a48400
	s_addc_u32 s1, s3, 0
	v_writelane_b32 v253, s0, 23
	v_mov_b32_e32 v1, 0
	v_mov_b32_e32 v167, 0x358637bd
	v_writelane_b32 v253, s1, 24
	s_add_u32 s0, s2, 0x11a48500
	s_addc_u32 s1, s3, 0
	v_writelane_b32 v253, s0, 25
	v_mov_b32_e32 v168, 0x3c0881c4
	v_mov_b32_e32 v169, 0xbab64f3b
	v_writelane_b32 v253, s1, 26
	s_add_u32 s0, s2, 0x11a48600
	s_addc_u32 s1, s3, 0
	v_writelane_b32 v253, s0, 27
	v_mov_b32_e32 v170, 0x3ca908c9
	v_mov_b32_e32 v171, 1
	v_writelane_b32 v253, s1, 28
	s_add_u32 s0, s2, 0x11a48700
	s_addc_u32 s1, s3, 0
	v_writelane_b32 v253, s0, 29
	v_add_u32_e32 v173, 64, v2
	v_xor_b32_e32 v174, 32, v172
	v_writelane_b32 v253, s1, 30
	s_add_u32 s0, s2, 0x11a48800
	s_addc_u32 s1, s3, 0
	v_writelane_b32 v253, s0, 31
	v_xor_b32_e32 v175, 16, v172
	v_xor_b32_e32 v193, 2, v172
	v_writelane_b32 v253, s1, 32
	s_add_u32 s0, s2, 0x11a48900
	s_addc_u32 s1, s3, 0
	v_writelane_b32 v253, s0, 33
	v_xor_b32_e32 v252, 1, v172
	v_mov_b32_e32 v180, 0xbe48000
	v_writelane_b32 v253, s1, 34
	s_add_u32 s0, s2, 0x11a48a00
	s_addc_u32 s1, s3, 0
	v_writelane_b32 v253, s0, 35
	v_mov_b32_e32 v181, 0xab48000
	v_mov_b32_e32 v182, 0xd848000
	v_writelane_b32 v253, s1, 36
	s_add_u32 s0, s2, 0x11a48b00
	s_addc_u32 s1, s3, 0
	v_writelane_b32 v253, s0, 37
	v_mov_b32_e32 v183, 0xb1c8000
	v_mov_b32_e32 v184, 0x2c00
	v_writelane_b32 v253, s1, 38
	s_add_u32 s0, s2, 0x11a48c00
	s_addc_u32 s1, s3, 0
	v_writelane_b32 v253, s0, 39
	v_mov_b32_e32 v185, 0x20be0
	v_mov_b32_e32 v186, 0x7f800000
	v_writelane_b32 v253, s1, 40
	s_add_u32 s0, s2, 0x11a48d00
	s_addc_u32 s1, s3, 0
	v_writelane_b32 v253, s0, 41
	v_not_b32_e32 v187, 63
	v_not_b32_e32 v188, 31
	v_writelane_b32 v253, s1, 42
	s_add_u32 s0, s2, 0x11a48e00
	s_addc_u32 s1, s3, 0
	v_writelane_b32 v253, s0, 43
	v_mov_b32_e32 v189, 0x7fc00000
	v_mov_b32_e32 v190, 0xffffff00
	v_writelane_b32 v253, s1, 44
	s_add_u32 s0, s2, 0x11a48f00
	s_addc_u32 s1, s3, 0
	v_writelane_b32 v253, s0, 45
	v_mov_b32_e32 v191, 0xfffffe80
	v_mov_b32_e32 v192, 3
	v_writelane_b32 v253, s1, 46
	s_add_u32 s0, s2, 0x11a49000
	s_addc_u32 s1, s3, 0
	v_writelane_b32 v253, s0, 47
	v_mov_b32_e32 v156, 0xf149f2ca
	s_movk_i32 s33, 0x6000
	v_writelane_b32 v253, s1, 48
	s_add_u32 s0, s2, 0x11a49100
	s_addc_u32 s1, s3, 0
	v_writelane_b32 v253, s0, 49
	s_movk_i32 s83, 0x2000
	s_movk_i32 s86, 0x1fff
	v_writelane_b32 v253, s1, 50
	s_add_u32 s0, s2, 0x11a49200
	s_addc_u32 s1, s3, 0
	v_writelane_b32 v253, s0, 51
	s_movk_i32 s77, 0x1000
	s_mov_b32 s70, 0x800000
	v_writelane_b32 v253, s1, 52
	s_add_u32 s0, s2, 0x11a49300
	s_addc_u32 s1, s3, 0
	v_writelane_b32 v253, s0, 53
	s_cmp_eq_u32 s10, 15
	s_movk_i32 s96, 0x5000
	v_writelane_b32 v253, s1, 54
	s_cselect_b64 s[0:1], -1, 0
	v_writelane_b32 v253, s0, 55
	s_cmp_eq_u32 s10, 14
	s_mov_b32 s50, 0x8000
	v_writelane_b32 v253, s1, 56
	s_cselect_b64 s[0:1], -1, 0
	v_writelane_b32 v253, s0, 57
	s_cmp_eq_u32 s10, 13
	s_movk_i32 s55, 0xff
	v_writelane_b32 v253, s1, 58
	s_cselect_b64 s[0:1], -1, 0
	v_writelane_b32 v253, s0, 59
	s_cmp_eq_u32 s10, 12
	s_mov_b32 s51, 0x40000
	v_writelane_b32 v253, s1, 60
	s_cselect_b64 s[0:1], -1, 0
	v_writelane_b32 v253, s0, 61
	s_cmp_eq_u32 s10, 11
	s_movk_i32 s48, 0x1200
	v_writelane_b32 v253, s1, 62
	s_cselect_b64 s[0:1], -1, 0
	v_writelane_b32 v253, s0, 63
	s_cmp_eq_u32 s10, 10
	s_movk_i32 s31, 0x7fff
	v_writelane_b32 v254, s1, 0
	s_cselect_b64 s[0:1], -1, 0
	v_writelane_b32 v254, s0, 1
	s_cmp_eq_u32 s10, 9
	s_movk_i32 s49, 0x3000
	v_writelane_b32 v254, s1, 2
	s_cselect_b64 s[0:1], -1, 0
	v_writelane_b32 v254, s0, 3
	s_cmp_eq_u32 s10, 8
	s_movk_i32 s56, 0x4000
	v_writelane_b32 v254, s1, 4
	s_cselect_b64 s[0:1], -1, 0
	v_writelane_b32 v254, s0, 5
	s_cmp_eq_u32 s10, 7
	s_mov_b32 s57, 0x27fff
	v_writelane_b32 v254, s1, 6
	s_cselect_b64 s[0:1], -1, 0
	v_writelane_b32 v254, s0, 7
	s_cmp_eq_u32 s10, 6
	s_movk_i32 s65, 0x400
	v_writelane_b32 v254, s1, 8
	s_cselect_b64 s[0:1], -1, 0
	v_writelane_b32 v254, s0, 9
	s_cmp_eq_u32 s10, 5
	s_mov_b32 s97, 0x12000
	v_writelane_b32 v254, s1, 10
	s_cselect_b64 s[0:1], -1, 0
	v_writelane_b32 v254, s0, 11
	s_cmp_eq_u32 s10, 4
	s_mov_b32 s87, 0xc000
	v_writelane_b32 v254, s1, 12
	s_cselect_b64 s[0:1], -1, 0
	v_writelane_b32 v254, s0, 13
	s_cmp_eq_u32 s10, 3
	s_movk_i32 s75, 0x404
	v_writelane_b32 v254, s1, 14
	s_cselect_b64 s[0:1], -1, 0
	v_writelane_b32 v254, s0, 15
	s_cmp_eq_u32 s10, 2
	s_mov_b32 s71, 0xc2ce8ed0
	v_writelane_b32 v254, s1, 16
	s_cselect_b64 s[0:1], -1, 0
	v_writelane_b32 v254, s0, 17
	s_cmp_eq_u32 s10, 1
	s_mov_b32 s30, 0x42b17218
	v_writelane_b32 v254, s1, 18
	s_cselect_b64 s[0:1], -1, 0
	v_writelane_b32 v254, s0, 19
	s_cmp_eq_u32 s10, 0
	s_mov_b32 s21, 0x437f0000
	v_writelane_b32 v254, s1, 20
	s_cselect_b64 s[0:1], -1, 0
	v_writelane_b32 v254, s0, 21
	s_mov_b32 s35, 0x3e38aa3b
	s_movk_i32 s58, 0x21ff
	v_writelane_b32 v254, s1, 22
	s_lshl_b32 s0, s10, 8
	s_add_u32 s0, s4, s0
	s_addc_u32 s1, s5, 0
	s_add_u32 s4, s0, 0x1400
	s_addc_u32 s5, s1, 0
	v_writelane_b32 v254, s4, 23
	s_add_u32 s0, s0, 0x2400
	s_addc_u32 s1, s1, 0
	v_writelane_b32 v254, s5, 24
	v_writelane_b32 v254, s0, 25
	s_mov_b32 s29, 0
	s_mov_b64 s[84:85], 0x800
	v_writelane_b32 v254, s1, 26
	s_add_u32 s0, s2, 0x11a4b400
	s_addc_u32 s1, s3, 0
	v_writelane_b32 v254, s0, 27
	s_mov_b64 s[24:25], 0x80
	s_mov_b32 s76, 0x3fb8aa3b
	v_writelane_b32 v254, s1, 28
	s_add_u32 s0, s2, 0x11a4b500
	s_addc_u32 s1, s3, 0
	v_writelane_b32 v254, s0, 29
	s_mov_b64 s[78:79], 0x1ff80
	s_mov_b32 s64, 0x3f803f80
	v_writelane_b32 v254, s1, 30
	s_movk_i32 s0, 0x3ff
	v_and_or_b32 v0, v0, s0, v166
	s_add_i32 s0, 0, 0x4400
	v_writelane_b32 v254, s0, 31
	s_add_i32 s0, 0, 0x6400
	v_writelane_b32 v254, s0, 32
	s_add_i32 s0, 0, 0xa400
	v_writelane_b32 v254, s0, 33
	s_add_i32 s0, 0, 0x11800
	v_writelane_b32 v254, s0, 34
	s_add_i32 s0, 0, 0x11000
	v_writelane_b32 v254, s0, 35
	s_add_i32 s0, 0, 0x21140
	v_writelane_b32 v254, s0, 36
	s_add_i32 s0, 0, 0x21144
	v_writelane_b32 v254, s0, 37
	v_readlane_b32 s0, v253, 2
	v_readlane_b32 s1, v253, 3
	s_nop 0
	v_writelane_b32 v254, s0, 38
	v_cmp_eq_u32_e64 s[0:1], 0, v0
	s_nop 1
	v_writelane_b32 v254, s0, 39
	s_nop 1
	v_writelane_b32 v254, s1, 40
	v_writelane_b32 v254, s53, 41
	v_writelane_b32 v254, s52, 42
	s_nop 1
	v_writelane_b32 v254, s53, 43
	v_writelane_b32 v254, s54, 44
	s_branch .LBB0_13

.LBB0_1792:
	s_andn2_b64 vcc, exec, s[0:1]
	s_cbranch_vccnz .LBB0_1903
	v_readlane_b32 s2, v253, 11
	v_readlane_b32 s3, v253, 12
	s_mov_b64 s[0:1], -1
	s_and_b64 vcc, exec, s[2:3]
	s_cbranch_vccz .LBB0_1830
	v_readlane_b32 s0, v253, 13
	v_readlane_b32 s1, v253, 14
	s_andn2_b64 vcc, exec, s[0:1]
	s_cbranch_vccnz .LBB0_1829
	s_sub_i32 s40, s89, 32
	s_add_u32 s0, s72, 0x1c80000
	s_addc_u32 s1, s73, 0
	s_add_u32 s2, s72, 0x1180000
	s_addc_u32 s3, s73, 0
	s_add_u32 s4, s72, 0x2200000
	s_addc_u32 s5, s73, 0
	s_add_u32 s6, s72, 0xf80000
	s_addc_u32 s7, s73, 0
	s_add_u32 s41, s72, 0xc80000
	s_addc_u32 s42, s73, 0
	s_add_u32 s8, s72, 0x100000
	s_addc_u32 s9, s73, 0
	v_readlane_b32 s43, v253, 15
	v_readlane_b32 s44, v255, 63
	s_cmp_eq_u32 s44, 1
	s_cbranch_scc0 .Lli_a
	v_readlane_b32 s43, v255, 22
	s_and_b32 s44, s43, 31
	s_lshr_b32 s43, s43, 5
	s_mul_i32 s43, s43, 12
	s_add_i32 s43, s43, s44
	s_add_i32 s43, s43, 0x2cc
	s_movk_i32 s40, 0x60
.Lli_a:
	s_branch .LBB0_1798
.LBB0_1796:
	s_or_b64 exec, exec, s[14:15]
.LBB0_1797:
	s_add_i32 s43, s40, s43
	v_readlane_b32 s44, v255, 63
	s_cmp_eq_u32 s44, 0
	s_cbranch_scc0 .Lli_b
	s_cmpk_lg_i32 s89, 0x100
	s_cbranch_scc1 .Lli_b
	s_cmpk_gt_i32 s43, 0x2df
	s_cbranch_scc1 .LBB0_1829
.Lli_b:
	s_cmpk_gt_i32 s43, 0x4ef
	s_cbranch_scc1 .LBB0_1829

.Ldt_done:
	s_cmpk_lg_i32 s89, 0x100
	s_cbranch_scc1 .Lli_done
	v_readlane_b32 s3, v255, 22
	s_and_b32 s3, s3, 31
	s_cmpk_lt_i32 s3, 20
	s_cbranch_scc1 .Lli_done
	v_readlane_b32 s3, v255, 63
	s_cmp_eq_u32 s2, 2
	s_cbranch_scc0 .Lli_n2
	s_cmp_eq_u32 s3, 0
	s_cbranch_scc0 .Lli_done
	s_mov_b32 s3, 1
	s_nop 0
	v_writelane_b32 v255, s3, 63
	s_mov_b32 s16, 0
	s_mov_b64 s[0:1], 0
	s_branch .LBB0_1969
.Lli_n2:
	s_cmp_eq_u32 s2, 0
	s_cbranch_scc0 .Lli_done
	s_cmp_eq_u32 s3, 1
	s_cbranch_scc0 .Lli_done
	s_mov_b32 s3, 2
	s_nop 0
	v_writelane_b32 v255, s3, 63
	s_mov_b32 s16, 3
